# weight transposes + rope table moved behind the norm pass (first seam waits only for the adaLN GEMV)
# baseline (speedup 1.0000x reference)
.Lp0a_gemv_done:
	s_lshl_b32 s49, s2, 3
	s_lshl_b32 s48, s46, 3

.Lp0a_tail:
	v_mov_b32_e32 v4, v198
	s_nop 0
	v_readfirstlane_b32 s3, v4
	s_ashr_i32 s22, s3, 6
	v_and_b32_e32 v1, 63, v4

.Lp0a_tail_done:
	v_cmp_eq_u32_e64 s[34:35], 0, v198
